# s_setprio 1 around QK and PV MFMA clusters, 0 during exp, in the three diff-attention loop copies
# speedup vs baseline: 1.0025x; 1.0025x over previous
.Ldf_dmadone0:
	s_setprio 1
	ds_read_b128 v[0:3], v128
	ds_read_b128 v[4:7], v128 offset:4096
	ds_read_b128 v[8:11], v129
	ds_read_b128 v[12:15], v129 offset:4096
	s_waitcnt lgkmcnt(2)
	v_mfma_f32_32x32x16_bf16 v[96:111], v[0:3], v[124:127], v[234:249]
	v_mfma_f32_32x32x16_bf16 v[80:95], v[4:7], v[124:127], v[234:249]
	ds_read_b128 v[0:3], v130
	ds_read_b128 v[4:7], v130 offset:4096
	s_waitcnt lgkmcnt(2)
	v_mfma_f32_32x32x16_bf16 v[96:111], v[8:11], v[120:123], v[96:111]
	v_mfma_f32_32x32x16_bf16 v[80:95], v[12:15], v[120:123], v[80:95]
	ds_read_b128 v[8:11], v131
	ds_read_b128 v[12:15], v131 offset:4096
	ds_read_b128 v[140:143], v132
	ds_read_b128 v[144:147], v132 offset:4096
	ds_read_b128 v[148:151], v132 offset:8192
	ds_read_b128 v[152:155], v132 offset:12288
	s_waitcnt lgkmcnt(6)
	v_mfma_f32_32x32x16_bf16 v[96:111], v[0:3], v[116:119], v[96:111]
	v_mfma_f32_32x32x16_bf16 v[80:95], v[4:7], v[116:119], v[80:95]
	s_waitcnt lgkmcnt(4)
	v_mfma_f32_32x32x16_bf16 v[96:111], v[8:11], v[112:115], v[96:111]
	v_mfma_f32_32x32x16_bf16 v[80:95], v[12:15], v[112:115], v[80:95]
	ds_read_b128 v[0:3], v133
	ds_read_b128 v[4:7], v133 offset:4096
	ds_read_b128 v[8:11], v133 offset:8192
	ds_read_b128 v[12:15], v133 offset:12288
.Ldf_exps0:
	s_setprio 0
	s_nop 6
	v_exp_f32_e32 v96, v96
	v_exp_f32_e32 v97, v97
	v_exp_f32_e32 v98, v98
	v_exp_f32_e32 v99, v99
	v_exp_f32_e32 v100, v100
	v_exp_f32_e32 v101, v101
	v_exp_f32_e32 v102, v102
	v_exp_f32_e32 v103, v103
	v_exp_f32_e32 v104, v104
	v_exp_f32_e32 v105, v105
	v_add_f32_e32 v156, v96, v98
	v_add_f32_e32 v157, v97, v99
	v_exp_f32_e32 v106, v106
	v_exp_f32_e32 v107, v107
	v_add_f32_e32 v156, v156, v100
	v_add_f32_e32 v157, v157, v101
	v_exp_f32_e32 v108, v108
	v_exp_f32_e32 v109, v109
	v_add_f32_e32 v156, v156, v102
	v_add_f32_e32 v157, v157, v103
	v_exp_f32_e32 v110, v110
	v_exp_f32_e32 v111, v111
	v_add_f32_e32 v156, v156, v104
	v_add_f32_e32 v157, v157, v105
	v_exp_f32_e32 v80, v80
	v_exp_f32_e32 v81, v81
	v_add_f32_e32 v156, v156, v106
	v_add_f32_e32 v157, v157, v107
	v_exp_f32_e32 v82, v82
	v_exp_f32_e32 v83, v83
	v_add_f32_e32 v156, v156, v108
	v_add_f32_e32 v157, v157, v109
	v_exp_f32_e32 v84, v84
	v_exp_f32_e32 v85, v85
	v_add_f32_e32 v156, v156, v110
	v_add_f32_e32 v157, v157, v111
	v_exp_f32_e32 v86, v86
	v_exp_f32_e32 v87, v87
	v_add_f32_e32 v156, v156, v80
	v_add_f32_e32 v157, v157, v81
	v_exp_f32_e32 v88, v88
	v_exp_f32_e32 v89, v89
	v_add_f32_e32 v156, v156, v82
	v_add_f32_e32 v157, v157, v83
	v_exp_f32_e32 v90, v90
	v_exp_f32_e32 v91, v91
	v_add_f32_e32 v156, v156, v84
	v_add_f32_e32 v157, v157, v85
	v_exp_f32_e32 v92, v92
	v_exp_f32_e32 v93, v93
	v_add_f32_e32 v156, v156, v86
	v_add_f32_e32 v157, v157, v87
	v_exp_f32_e32 v94, v94
	v_exp_f32_e32 v95, v95
	v_add_f32_e32 v156, v156, v88
	v_add_f32_e32 v157, v157, v89
	v_add_f32_e32 v156, v156, v90
	v_add_f32_e32 v157, v157, v91
	v_add_f32_e32 v156, v156, v92
	v_add_f32_e32 v157, v157, v93
	v_add_f32_e32 v156, v156, v94
	v_add_f32_e32 v157, v157, v95
	v_add_f32_e32 v156, v156, v157
	v_cmp_lt_f32_e32 vcc, s100, v156
	s_cbranch_vccnz .Ldf_fixin0
	s_setprio 1
	v_add_f32_e32 v180, v180, v156
	v_cvt_pk_bf16_f32 v96, v96, v97
	v_cvt_pk_bf16_f32 v97, v98, v99
	v_cvt_pk_bf16_f32 v98, v100, v101
	v_cvt_pk_bf16_f32 v99, v102, v103
	s_waitcnt lgkmcnt(4)
	s_nop 0
	v_mfma_f32_32x32x16_bf16 v[64:79], v[140:143], v[96:99], v[64:79]
	v_cvt_pk_bf16_f32 v104, v104, v105
	v_mfma_f32_32x32x16_bf16 v[48:63], v[144:147], v[96:99], v[48:63]
	v_cvt_pk_bf16_f32 v105, v106, v107
	v_mfma_f32_32x32x16_bf16 v[32:47], v[148:151], v[96:99], v[32:47]
	v_cvt_pk_bf16_f32 v106, v108, v109
	v_mfma_f32_32x32x16_bf16 v[16:31], v[152:155], v[96:99], v[16:31]
	v_cvt_pk_bf16_f32 v107, v110, v111
	ds_read_b128 v[140:143], v134
	ds_read_b128 v[144:147], v134 offset:4096
	ds_read_b128 v[148:151], v134 offset:8192
	ds_read_b128 v[152:155], v134 offset:12288
	s_waitcnt lgkmcnt(4)
	v_mfma_f32_32x32x16_bf16 v[64:79], v[0:3], v[104:107], v[64:79]
	v_cvt_pk_bf16_f32 v80, v80, v81
	v_mfma_f32_32x32x16_bf16 v[48:63], v[4:7], v[104:107], v[48:63]
	v_cvt_pk_bf16_f32 v81, v82, v83
	v_mfma_f32_32x32x16_bf16 v[32:47], v[8:11], v[104:107], v[32:47]
	v_cvt_pk_bf16_f32 v82, v84, v85
	v_mfma_f32_32x32x16_bf16 v[16:31], v[12:15], v[104:107], v[16:31]
	v_cvt_pk_bf16_f32 v83, v86, v87
	ds_read_b128 v[0:3], v135
	ds_read_b128 v[4:7], v135 offset:4096
	ds_read_b128 v[8:11], v135 offset:8192
	ds_read_b128 v[12:15], v135 offset:12288
	s_waitcnt lgkmcnt(4)
	v_mfma_f32_32x32x16_bf16 v[64:79], v[140:143], v[80:83], v[64:79]
	v_cvt_pk_bf16_f32 v88, v88, v89
	v_mfma_f32_32x32x16_bf16 v[48:63], v[144:147], v[80:83], v[48:63]
	v_cvt_pk_bf16_f32 v89, v90, v91
	v_mfma_f32_32x32x16_bf16 v[32:47], v[148:151], v[80:83], v[32:47]
	v_cvt_pk_bf16_f32 v90, v92, v93
	v_mfma_f32_32x32x16_bf16 v[16:31], v[152:155], v[80:83], v[16:31]
	v_cvt_pk_bf16_f32 v91, v94, v95
	s_waitcnt lgkmcnt(0)
	s_nop 0
	v_mfma_f32_32x32x16_bf16 v[64:79], v[0:3], v[88:91], v[64:79]
	v_mfma_f32_32x32x16_bf16 v[48:63], v[4:7], v[88:91], v[48:63]
	v_mfma_f32_32x32x16_bf16 v[32:47], v[8:11], v[88:91], v[32:47]
	v_mfma_f32_32x32x16_bf16 v[16:31], v[12:15], v[88:91], v[16:31]
	s_setprio 0
	s_add_i32 s31, s31, 1
	s_waitcnt vmcnt(3)
	s_waitcnt lgkmcnt(0)
	s_barrier
	s_cmp_lg_u32 s31, s20
	s_cbranch_scc0 .Ldf_exit0

.Ldf_dmadone1:
	s_setprio 1
	ds_read_b128 v[0:3], v128 offset:24576
	ds_read_b128 v[4:7], v128 offset:28672
	ds_read_b128 v[8:11], v129 offset:24576
	ds_read_b128 v[12:15], v129 offset:28672
	s_waitcnt lgkmcnt(2)
	v_mfma_f32_32x32x16_bf16 v[96:111], v[0:3], v[124:127], v[234:249]
	v_mfma_f32_32x32x16_bf16 v[80:95], v[4:7], v[124:127], v[234:249]
	ds_read_b128 v[0:3], v130 offset:24576
	ds_read_b128 v[4:7], v130 offset:28672
	s_waitcnt lgkmcnt(2)
	v_mfma_f32_32x32x16_bf16 v[96:111], v[8:11], v[120:123], v[96:111]
	v_mfma_f32_32x32x16_bf16 v[80:95], v[12:15], v[120:123], v[80:95]
	ds_read_b128 v[8:11], v131 offset:24576
	ds_read_b128 v[12:15], v131 offset:28672
	ds_read_b128 v[140:143], v132 offset:24576
	ds_read_b128 v[144:147], v132 offset:28672
	ds_read_b128 v[148:151], v132 offset:32768
	ds_read_b128 v[152:155], v132 offset:36864
	s_waitcnt lgkmcnt(6)
	v_mfma_f32_32x32x16_bf16 v[96:111], v[0:3], v[116:119], v[96:111]
	v_mfma_f32_32x32x16_bf16 v[80:95], v[4:7], v[116:119], v[80:95]
	s_waitcnt lgkmcnt(4)
	v_mfma_f32_32x32x16_bf16 v[96:111], v[8:11], v[112:115], v[96:111]
	v_mfma_f32_32x32x16_bf16 v[80:95], v[12:15], v[112:115], v[80:95]
	ds_read_b128 v[0:3], v133 offset:24576
	ds_read_b128 v[4:7], v133 offset:28672
	ds_read_b128 v[8:11], v133 offset:32768
	ds_read_b128 v[12:15], v133 offset:36864
.Ldf_exps1:
	s_setprio 0
	s_nop 6
	v_exp_f32_e32 v96, v96
	v_exp_f32_e32 v97, v97
	v_exp_f32_e32 v98, v98
	v_exp_f32_e32 v99, v99
	v_exp_f32_e32 v100, v100
	v_exp_f32_e32 v101, v101
	v_exp_f32_e32 v102, v102
	v_exp_f32_e32 v103, v103
	v_exp_f32_e32 v104, v104
	v_exp_f32_e32 v105, v105
	v_add_f32_e32 v156, v96, v98
	v_add_f32_e32 v157, v97, v99
	v_exp_f32_e32 v106, v106
	v_exp_f32_e32 v107, v107
	v_add_f32_e32 v156, v156, v100
	v_add_f32_e32 v157, v157, v101
	v_exp_f32_e32 v108, v108
	v_exp_f32_e32 v109, v109
	v_add_f32_e32 v156, v156, v102
	v_add_f32_e32 v157, v157, v103
	v_exp_f32_e32 v110, v110
	v_exp_f32_e32 v111, v111
	v_add_f32_e32 v156, v156, v104
	v_add_f32_e32 v157, v157, v105
	v_exp_f32_e32 v80, v80
	v_exp_f32_e32 v81, v81
	v_add_f32_e32 v156, v156, v106
	v_add_f32_e32 v157, v157, v107
	v_exp_f32_e32 v82, v82
	v_exp_f32_e32 v83, v83
	v_add_f32_e32 v156, v156, v108
	v_add_f32_e32 v157, v157, v109
	v_exp_f32_e32 v84, v84
	v_exp_f32_e32 v85, v85
	v_add_f32_e32 v156, v156, v110
	v_add_f32_e32 v157, v157, v111
	v_exp_f32_e32 v86, v86
	v_exp_f32_e32 v87, v87
	v_add_f32_e32 v156, v156, v80
	v_add_f32_e32 v157, v157, v81
	v_exp_f32_e32 v88, v88
	v_exp_f32_e32 v89, v89
	v_add_f32_e32 v156, v156, v82
	v_add_f32_e32 v157, v157, v83
	v_exp_f32_e32 v90, v90
	v_exp_f32_e32 v91, v91
	v_add_f32_e32 v156, v156, v84
	v_add_f32_e32 v157, v157, v85
	v_exp_f32_e32 v92, v92
	v_exp_f32_e32 v93, v93
	v_add_f32_e32 v156, v156, v86
	v_add_f32_e32 v157, v157, v87
	v_exp_f32_e32 v94, v94
	v_exp_f32_e32 v95, v95
	v_add_f32_e32 v156, v156, v88
	v_add_f32_e32 v157, v157, v89
	v_add_f32_e32 v156, v156, v90
	v_add_f32_e32 v157, v157, v91
	v_add_f32_e32 v156, v156, v92
	v_add_f32_e32 v157, v157, v93
	v_add_f32_e32 v156, v156, v94
	v_add_f32_e32 v157, v157, v95
	v_add_f32_e32 v156, v156, v157
	v_cmp_lt_f32_e32 vcc, s100, v156
	s_cbranch_vccnz .Ldf_fixin1
	s_setprio 1
	v_add_f32_e32 v180, v180, v156
	v_cvt_pk_bf16_f32 v96, v96, v97
	v_cvt_pk_bf16_f32 v97, v98, v99
	v_cvt_pk_bf16_f32 v98, v100, v101
	v_cvt_pk_bf16_f32 v99, v102, v103
	s_waitcnt lgkmcnt(4)
	s_nop 0
	v_mfma_f32_32x32x16_bf16 v[64:79], v[140:143], v[96:99], v[64:79]
	v_cvt_pk_bf16_f32 v104, v104, v105
	v_mfma_f32_32x32x16_bf16 v[48:63], v[144:147], v[96:99], v[48:63]
	v_cvt_pk_bf16_f32 v105, v106, v107
	v_mfma_f32_32x32x16_bf16 v[32:47], v[148:151], v[96:99], v[32:47]
	v_cvt_pk_bf16_f32 v106, v108, v109
	v_mfma_f32_32x32x16_bf16 v[16:31], v[152:155], v[96:99], v[16:31]
	v_cvt_pk_bf16_f32 v107, v110, v111
	ds_read_b128 v[140:143], v134 offset:24576
	ds_read_b128 v[144:147], v134 offset:28672
	ds_read_b128 v[148:151], v134 offset:32768
	ds_read_b128 v[152:155], v134 offset:36864
	s_waitcnt lgkmcnt(4)
	v_mfma_f32_32x32x16_bf16 v[64:79], v[0:3], v[104:107], v[64:79]
	v_cvt_pk_bf16_f32 v80, v80, v81
	v_mfma_f32_32x32x16_bf16 v[48:63], v[4:7], v[104:107], v[48:63]
	v_cvt_pk_bf16_f32 v81, v82, v83
	v_mfma_f32_32x32x16_bf16 v[32:47], v[8:11], v[104:107], v[32:47]
	v_cvt_pk_bf16_f32 v82, v84, v85
	v_mfma_f32_32x32x16_bf16 v[16:31], v[12:15], v[104:107], v[16:31]
	v_cvt_pk_bf16_f32 v83, v86, v87
	ds_read_b128 v[0:3], v135 offset:24576
	ds_read_b128 v[4:7], v135 offset:28672
	ds_read_b128 v[8:11], v135 offset:32768
	ds_read_b128 v[12:15], v135 offset:36864
	s_waitcnt lgkmcnt(4)
	v_mfma_f32_32x32x16_bf16 v[64:79], v[140:143], v[80:83], v[64:79]
	v_cvt_pk_bf16_f32 v88, v88, v89
	v_mfma_f32_32x32x16_bf16 v[48:63], v[144:147], v[80:83], v[48:63]
	v_cvt_pk_bf16_f32 v89, v90, v91
	v_mfma_f32_32x32x16_bf16 v[32:47], v[148:151], v[80:83], v[32:47]
	v_cvt_pk_bf16_f32 v90, v92, v93
	v_mfma_f32_32x32x16_bf16 v[16:31], v[152:155], v[80:83], v[16:31]
	v_cvt_pk_bf16_f32 v91, v94, v95
	s_waitcnt lgkmcnt(0)
	s_nop 0
	v_mfma_f32_32x32x16_bf16 v[64:79], v[0:3], v[88:91], v[64:79]
	v_mfma_f32_32x32x16_bf16 v[48:63], v[4:7], v[88:91], v[48:63]
	v_mfma_f32_32x32x16_bf16 v[32:47], v[8:11], v[88:91], v[32:47]
	v_mfma_f32_32x32x16_bf16 v[16:31], v[12:15], v[88:91], v[16:31]
	s_setprio 0
	s_add_i32 s31, s31, 1
	s_waitcnt vmcnt(3)
	s_waitcnt lgkmcnt(0)
	s_barrier
	s_cmp_lg_u32 s31, s20
	s_cbranch_scc0 .Ldf_exit1

.Ldf_dmadone2:
	s_setprio 1
	ds_read_b128 v[0:3], v128 offset:49152
	ds_read_b128 v[4:7], v128 offset:53248
	ds_read_b128 v[8:11], v129 offset:49152
	ds_read_b128 v[12:15], v129 offset:53248
	s_waitcnt lgkmcnt(2)
	v_mfma_f32_32x32x16_bf16 v[96:111], v[0:3], v[124:127], v[234:249]
	v_mfma_f32_32x32x16_bf16 v[80:95], v[4:7], v[124:127], v[234:249]
	ds_read_b128 v[0:3], v130 offset:49152
	ds_read_b128 v[4:7], v130 offset:53248
	s_waitcnt lgkmcnt(2)
	v_mfma_f32_32x32x16_bf16 v[96:111], v[8:11], v[120:123], v[96:111]
	v_mfma_f32_32x32x16_bf16 v[80:95], v[12:15], v[120:123], v[80:95]
	ds_read_b128 v[8:11], v131 offset:49152
	ds_read_b128 v[12:15], v131 offset:53248
	ds_read_b128 v[140:143], v132 offset:49152
	ds_read_b128 v[144:147], v132 offset:53248
	ds_read_b128 v[148:151], v132 offset:57344
	ds_read_b128 v[152:155], v132 offset:61440
	s_waitcnt lgkmcnt(6)
	v_mfma_f32_32x32x16_bf16 v[96:111], v[0:3], v[116:119], v[96:111]
	v_mfma_f32_32x32x16_bf16 v[80:95], v[4:7], v[116:119], v[80:95]
	s_waitcnt lgkmcnt(4)
	v_mfma_f32_32x32x16_bf16 v[96:111], v[8:11], v[112:115], v[96:111]
	v_mfma_f32_32x32x16_bf16 v[80:95], v[12:15], v[112:115], v[80:95]
	ds_read_b128 v[0:3], v133 offset:49152
	ds_read_b128 v[4:7], v133 offset:53248
	ds_read_b128 v[8:11], v133 offset:57344
	ds_read_b128 v[12:15], v133 offset:61440
.Ldf_exps2:
	s_setprio 0
	s_nop 6
	v_exp_f32_e32 v96, v96
	v_exp_f32_e32 v97, v97
	v_exp_f32_e32 v98, v98
	v_exp_f32_e32 v99, v99
	v_exp_f32_e32 v100, v100
	v_exp_f32_e32 v101, v101
	v_exp_f32_e32 v102, v102
	v_exp_f32_e32 v103, v103
	v_exp_f32_e32 v104, v104
	v_exp_f32_e32 v105, v105
	v_add_f32_e32 v156, v96, v98
	v_add_f32_e32 v157, v97, v99
	v_exp_f32_e32 v106, v106
	v_exp_f32_e32 v107, v107
	v_add_f32_e32 v156, v156, v100
	v_add_f32_e32 v157, v157, v101
	v_exp_f32_e32 v108, v108
	v_exp_f32_e32 v109, v109
	v_add_f32_e32 v156, v156, v102
	v_add_f32_e32 v157, v157, v103
	v_exp_f32_e32 v110, v110
	v_exp_f32_e32 v111, v111
	v_add_f32_e32 v156, v156, v104
	v_add_f32_e32 v157, v157, v105
	v_exp_f32_e32 v80, v80
	v_exp_f32_e32 v81, v81
	v_add_f32_e32 v156, v156, v106
	v_add_f32_e32 v157, v157, v107
	v_exp_f32_e32 v82, v82
	v_exp_f32_e32 v83, v83
	v_add_f32_e32 v156, v156, v108
	v_add_f32_e32 v157, v157, v109
	v_exp_f32_e32 v84, v84
	v_exp_f32_e32 v85, v85
	v_add_f32_e32 v156, v156, v110
	v_add_f32_e32 v157, v157, v111
	v_exp_f32_e32 v86, v86
	v_exp_f32_e32 v87, v87
	v_add_f32_e32 v156, v156, v80
	v_add_f32_e32 v157, v157, v81
	v_exp_f32_e32 v88, v88
	v_exp_f32_e32 v89, v89
	v_add_f32_e32 v156, v156, v82
	v_add_f32_e32 v157, v157, v83
	v_exp_f32_e32 v90, v90
	v_exp_f32_e32 v91, v91
	v_add_f32_e32 v156, v156, v84
	v_add_f32_e32 v157, v157, v85
	v_exp_f32_e32 v92, v92
	v_exp_f32_e32 v93, v93
	v_add_f32_e32 v156, v156, v86
	v_add_f32_e32 v157, v157, v87
	v_exp_f32_e32 v94, v94
	v_exp_f32_e32 v95, v95
	v_add_f32_e32 v156, v156, v88
	v_add_f32_e32 v157, v157, v89
	v_add_f32_e32 v156, v156, v90
	v_add_f32_e32 v157, v157, v91
	v_add_f32_e32 v156, v156, v92
	v_add_f32_e32 v157, v157, v93
	v_add_f32_e32 v156, v156, v94
	v_add_f32_e32 v157, v157, v95
	v_add_f32_e32 v156, v156, v157
	v_cmp_lt_f32_e32 vcc, s100, v156
	s_cbranch_vccnz .Ldf_fixin2
	s_setprio 1
	v_add_f32_e32 v180, v180, v156
	v_cvt_pk_bf16_f32 v96, v96, v97
	v_cvt_pk_bf16_f32 v97, v98, v99
	v_cvt_pk_bf16_f32 v98, v100, v101
	v_cvt_pk_bf16_f32 v99, v102, v103
	s_waitcnt lgkmcnt(4)
	s_nop 0
	v_mfma_f32_32x32x16_bf16 v[64:79], v[140:143], v[96:99], v[64:79]
	v_cvt_pk_bf16_f32 v104, v104, v105
	v_mfma_f32_32x32x16_bf16 v[48:63], v[144:147], v[96:99], v[48:63]
	v_cvt_pk_bf16_f32 v105, v106, v107
	v_mfma_f32_32x32x16_bf16 v[32:47], v[148:151], v[96:99], v[32:47]
	v_cvt_pk_bf16_f32 v106, v108, v109
	v_mfma_f32_32x32x16_bf16 v[16:31], v[152:155], v[96:99], v[16:31]
	v_cvt_pk_bf16_f32 v107, v110, v111
	ds_read_b128 v[140:143], v134 offset:49152
	ds_read_b128 v[144:147], v134 offset:53248
	ds_read_b128 v[148:151], v134 offset:57344
	ds_read_b128 v[152:155], v134 offset:61440
	s_waitcnt lgkmcnt(4)
	v_mfma_f32_32x32x16_bf16 v[64:79], v[0:3], v[104:107], v[64:79]
	v_cvt_pk_bf16_f32 v80, v80, v81
	v_mfma_f32_32x32x16_bf16 v[48:63], v[4:7], v[104:107], v[48:63]
	v_cvt_pk_bf16_f32 v81, v82, v83
	v_mfma_f32_32x32x16_bf16 v[32:47], v[8:11], v[104:107], v[32:47]
	v_cvt_pk_bf16_f32 v82, v84, v85
	v_mfma_f32_32x32x16_bf16 v[16:31], v[12:15], v[104:107], v[16:31]
	v_cvt_pk_bf16_f32 v83, v86, v87
	ds_read_b128 v[0:3], v135 offset:49152
	ds_read_b128 v[4:7], v135 offset:53248
	ds_read_b128 v[8:11], v135 offset:57344
	ds_read_b128 v[12:15], v135 offset:61440
	s_waitcnt lgkmcnt(4)
	v_mfma_f32_32x32x16_bf16 v[64:79], v[140:143], v[80:83], v[64:79]
	v_cvt_pk_bf16_f32 v88, v88, v89
	v_mfma_f32_32x32x16_bf16 v[48:63], v[144:147], v[80:83], v[48:63]
	v_cvt_pk_bf16_f32 v89, v90, v91
	v_mfma_f32_32x32x16_bf16 v[32:47], v[148:151], v[80:83], v[32:47]
	v_cvt_pk_bf16_f32 v90, v92, v93
	v_mfma_f32_32x32x16_bf16 v[16:31], v[152:155], v[80:83], v[16:31]
	v_cvt_pk_bf16_f32 v91, v94, v95
	s_waitcnt lgkmcnt(0)
	s_nop 0
	v_mfma_f32_32x32x16_bf16 v[64:79], v[0:3], v[88:91], v[64:79]
	v_mfma_f32_32x32x16_bf16 v[48:63], v[4:7], v[88:91], v[48:63]
	v_mfma_f32_32x32x16_bf16 v[32:47], v[8:11], v[88:91], v[32:47]
	v_mfma_f32_32x32x16_bf16 v[16:31], v[12:15], v[88:91], v[16:31]
	s_setprio 0
	s_add_i32 s31, s31, 1
	s_waitcnt vmcnt(3)
	s_waitcnt lgkmcnt(0)
	s_barrier
	s_cmp_lg_u32 s31, s20
	s_cbranch_scc0 .Ldf_exit2
	s_branch .LBB0_296
